# phase-0 channel-DFT fold items: the 16 weight-tile loads of the staging loop issued together with one wait (was two loads plus a full wait per iteration, 8 serialized round trips)
# speedup vs baseline: 1.0036x; 1.0036x over previous
.LBB0_1286:
	v_ashrrev_i32_e32 v3, 7, v6
	v_ashrrev_i32_e32 v12, 7, v7
	v_add_u32_e32 v3, s61, v3
	v_add_u32_e32 v14, s64, v12
	v_mad_i64_i32 v[12:13], s[36:37], v3, s86, v[4:5]
	v_mad_i64_i32 v[14:15], s[36:37], v14, s86, v[4:5]
	global_load_dword v100, v[12:13], off
	s_nop 0
	global_load_dword v101, v[14:15], off
	v_add_u32_e32 v7, 0x200, v7
	v_add_u32_e32 v6, 0x200, v6
	v_ashrrev_i32_e32 v3, 7, v6
	v_ashrrev_i32_e32 v12, 7, v7
	v_add_u32_e32 v3, s61, v3
	v_add_u32_e32 v14, s64, v12
	v_mad_i64_i32 v[12:13], s[36:37], v3, s86, v[4:5]
	v_mad_i64_i32 v[14:15], s[36:37], v14, s86, v[4:5]
	global_load_dword v102, v[12:13], off
	s_nop 0
	global_load_dword v103, v[14:15], off
	v_add_u32_e32 v7, 0x200, v7
	v_add_u32_e32 v6, 0x200, v6
	v_ashrrev_i32_e32 v3, 7, v6
	v_ashrrev_i32_e32 v12, 7, v7
	v_add_u32_e32 v3, s61, v3
	v_add_u32_e32 v14, s64, v12
	v_mad_i64_i32 v[12:13], s[36:37], v3, s86, v[4:5]
	v_mad_i64_i32 v[14:15], s[36:37], v14, s86, v[4:5]
	global_load_dword v104, v[12:13], off
	s_nop 0
	global_load_dword v105, v[14:15], off
	v_add_u32_e32 v7, 0x200, v7
	v_add_u32_e32 v6, 0x200, v6
	v_ashrrev_i32_e32 v3, 7, v6
	v_ashrrev_i32_e32 v12, 7, v7
	v_add_u32_e32 v3, s61, v3
	v_add_u32_e32 v14, s64, v12
	v_mad_i64_i32 v[12:13], s[36:37], v3, s86, v[4:5]
	v_mad_i64_i32 v[14:15], s[36:37], v14, s86, v[4:5]
	global_load_dword v106, v[12:13], off
	s_nop 0
	global_load_dword v107, v[14:15], off
	v_add_u32_e32 v7, 0x200, v7
	v_add_u32_e32 v6, 0x200, v6
	v_ashrrev_i32_e32 v3, 7, v6
	v_ashrrev_i32_e32 v12, 7, v7
	v_add_u32_e32 v3, s61, v3
	v_add_u32_e32 v14, s64, v12
	v_mad_i64_i32 v[12:13], s[36:37], v3, s86, v[4:5]
	v_mad_i64_i32 v[14:15], s[36:37], v14, s86, v[4:5]
	global_load_dword v108, v[12:13], off
	s_nop 0
	global_load_dword v109, v[14:15], off
	v_add_u32_e32 v7, 0x200, v7
	v_add_u32_e32 v6, 0x200, v6
	v_ashrrev_i32_e32 v3, 7, v6
	v_ashrrev_i32_e32 v12, 7, v7
	v_add_u32_e32 v3, s61, v3
	v_add_u32_e32 v14, s64, v12
	v_mad_i64_i32 v[12:13], s[36:37], v3, s86, v[4:5]
	v_mad_i64_i32 v[14:15], s[36:37], v14, s86, v[4:5]
	global_load_dword v110, v[12:13], off
	s_nop 0
	global_load_dword v111, v[14:15], off
	v_add_u32_e32 v7, 0x200, v7
	v_add_u32_e32 v6, 0x200, v6
	v_ashrrev_i32_e32 v3, 7, v6
	v_ashrrev_i32_e32 v12, 7, v7
	v_add_u32_e32 v3, s61, v3
	v_add_u32_e32 v14, s64, v12
	v_mad_i64_i32 v[12:13], s[36:37], v3, s86, v[4:5]
	v_mad_i64_i32 v[14:15], s[36:37], v14, s86, v[4:5]
	global_load_dword v112, v[12:13], off
	s_nop 0
	global_load_dword v113, v[14:15], off
	v_add_u32_e32 v7, 0x200, v7
	v_add_u32_e32 v6, 0x200, v6
	v_ashrrev_i32_e32 v3, 7, v6
	v_ashrrev_i32_e32 v12, 7, v7
	v_add_u32_e32 v3, s61, v3
	v_add_u32_e32 v14, s64, v12
	v_mad_i64_i32 v[12:13], s[36:37], v3, s86, v[4:5]
	v_mad_i64_i32 v[14:15], s[36:37], v14, s86, v[4:5]
	global_load_dword v114, v[12:13], off
	s_nop 0
	global_load_dword v115, v[14:15], off
	v_add_u32_e32 v7, 0x200, v7
	v_add_u32_e32 v6, 0x200, v6
	s_waitcnt vmcnt(0)
	ds_write2st64_b32 v10, v100, v101 offset1:4
	v_add_u32_e32 v10, 0x800, v10
	ds_write2st64_b32 v10, v102, v103 offset1:4
	v_add_u32_e32 v10, 0x800, v10
	ds_write2st64_b32 v10, v104, v105 offset1:4
	v_add_u32_e32 v10, 0x800, v10
	ds_write2st64_b32 v10, v106, v107 offset1:4
	v_add_u32_e32 v10, 0x800, v10
	ds_write2st64_b32 v10, v108, v109 offset1:4
	v_add_u32_e32 v10, 0x800, v10
	ds_write2st64_b32 v10, v110, v111 offset1:4
	v_add_u32_e32 v10, 0x800, v10
	ds_write2st64_b32 v10, v112, v113 offset1:4
	v_add_u32_e32 v10, 0x800, v10
	ds_write2st64_b32 v10, v114, v115 offset1:4
	v_add_u32_e32 v10, 0x800, v10
	v_mov_b32_e32 v11, 0
	s_or_b64 exec, exec, s[28:29]
	v_cmp_ne_u32_e32 vcc, v8, v9
	v_lshl_add_u32 v3, v9, 8, v2
	s_orn2_b64 s[28:29], vcc, exec
